# up-projection: first K iteration of every later unit runs from a copy with vmcnt(24) on its first two waits (epilogue stores stay in flight)
# speedup vs baseline: 1.0019x; 1.0003x over previous
; #define PG8_STAGE(bufoff, gbase, voff) do { _Pragma("unroll") for (int _i = 0; _i < 2; ++_i) \
;         __builtin_amdgcn_global_load_lds((const unsigned*)((const char*)(gbase) + (voff)[_i]), (PG8_LAS unsigned*)(lds + (bufoff) + ldsw + _i * 8192), 16, 0, 0); } while (0)
; #define PG8_LDA(dst, b, h) do { _Pragma("unroll") for (int m = 0; m < 4; ++m) _Pragma("unroll") for (int k = 0; k < 2; ++k) dst[m][k] = *(const PG8_LAS bf16x8*)(lds + PG8_SA(b, h) + aoff + m * 2048 + k * 1024); } while (0)
; #define PG8_LDB(dst, b, h) do { _Pragma("unroll") for (int n = 0; n < 2; ++n) _Pragma("unroll") for (int k = 0; k < 2; ++k) dst[n][k] = *(const PG8_LAS bf16x8*)(lds + PG8_SB(b, h) + boff + n * 2048 + k * 1024); } while (0)
; #define PG8_MMA(ai, bj, At, Bt) do { __builtin_amdgcn_s_setprio(1); _Pragma("unroll") for (int m = 0; m < 4; ++m) _Pragma("unroll") for (int n = 0; n < 2; ++n) _Pragma("unroll") for (int k = 0; k < 2; ++k) \
;         acc[ai][bj][m][n] = __builtin_amdgcn_mfma_f32_16x16x32_bf16(Bt[n][k], At[m][k], acc[ai][bj][m][n], 0, 0, 0); __builtin_amdgcn_s_setprio(0); } while (0)
; #define PG8_BAR __builtin_amdgcn_s_barrier()
; template <class Epi, class Sched, bool ALIGN_EPI = false, bool SP2 = false>
; __device__ __forceinline__ void gemm_phase(PG8_LAS unsigned char* lds, const Gemm g, const Sched& S, const Epi& E, const int wid) {
;     ...
;         for (int t = 0; t < nt; t += 2) {
;             const bool last = (t == nt - 2);
;             const char* a1 = cA + (size_t)(t + 1) * kstep;
;             const char* a2 = last ? nA : cA + (size_t)(t + 2) * kstep; const char* b2 = last ? nB : cB + (size_t)(t + 2) * kstep;
;             const char* a3 = a2 + kstep; const char* b3 = b2 + kstep;
;             if (last && has_next) S.a_ready(nxt);
;             if constexpr (SP2) {
;             PG8_LDB(B0, 0, 0); PG8_LDB(B1, 0, 1); PG8_SCHED; PG8_LDA(At, 0, 0); PG8_STAGE(PG8_SA(1, 1), a1 + hsA, voffA);
;             PG8_WAIT_V(8); PG8_WAIT_L(0); PG8_BAR; PG8_MMA(0, 0, At, B0); PG8_MMA(0, 1, At, B1); PG8_BAR; PG8_SCHED;
;     ...
; #pragma unroll
;         for (int a = 0; a < 2; ++a)
; #pragma unroll
;             for (int b = 0; b < 2; ++b)
; #pragma unroll
;                 for (int m = 0; m < 4; ++m)
; #pragma unroll
;                     for (int n = 0; n < 2; ++n) acc[a][b][m][n] = (f32x4){0.f, 0.f, 0.f, 0.f};
;         cur = nxt; cA = nA; cB = nB; ++ui;
.LBB0_1473:
	s_ashr_i32 s49, s48, 31
	s_lshl_b64 s[24:25], s[48:49], 19
	s_add_u32 s50, s3, s24
	s_addc_u32 s51, s4, s25
	s_and_b64 s[24:25], s[12:13], exec
	s_cselect_b32 s49, s51, s57
	s_cselect_b32 s65, s50, s56
	s_ashr_i32 s47, s46, 31
	s_lshl_b64 s[24:25], s[46:47], 19
	s_add_u32 s52, s5, s24
	s_addc_u32 s53, s10, s25
	s_and_b64 s[24:25], s[12:13], exec
	s_cselect_b32 s47, s53, s59
	s_cselect_b32 s66, s52, s58
	s_add_u32 s56, s56, 0x40080
	s_addc_u32 s57, s57, 0
	s_add_u32 s67, s58, 0x100
	v_mov_b32_e32 v2, 0
	s_addc_u32 s68, s59, 0
	s_mov_b32 s69, -2
	v_mov_b32_e32 v3, v2
	v_mov_b32_e32 v4, v2
	v_mov_b32_e32 v5, v2
	v_mov_b32_e32 v6, v2
	v_mov_b32_e32 v7, v2
	v_mov_b32_e32 v8, v2
	v_mov_b32_e32 v9, v2
	v_mov_b32_e32 v18, v2
	v_mov_b32_e32 v19, v2
	v_mov_b32_e32 v20, v2
	v_mov_b32_e32 v21, v2
	v_mov_b32_e32 v22, v2
	v_mov_b32_e32 v23, v2
	v_mov_b32_e32 v24, v2
	v_mov_b32_e32 v25, v2
	v_mov_b32_e32 v34, v2
	v_mov_b32_e32 v35, v2
	v_mov_b32_e32 v36, v2
	v_mov_b32_e32 v37, v2
	v_mov_b32_e32 v38, v2
	v_mov_b32_e32 v39, v2
	v_mov_b32_e32 v40, v2
	v_mov_b32_e32 v41, v2
	v_mov_b32_e32 v50, v2
	v_mov_b32_e32 v51, v2
	v_mov_b32_e32 v52, v2
	v_mov_b32_e32 v53, v2
	v_mov_b32_e32 v54, v2
	v_mov_b32_e32 v55, v2
	v_mov_b32_e32 v56, v2
	v_mov_b32_e32 v57, v2
	v_mov_b32_e32 v10, v2
	v_mov_b32_e32 v11, v2
	v_mov_b32_e32 v12, v2
	v_mov_b32_e32 v13, v2
	v_mov_b32_e32 v14, v2
	v_mov_b32_e32 v15, v2
	v_mov_b32_e32 v16, v2
	v_mov_b32_e32 v17, v2
	v_mov_b32_e32 v26, v2
	v_mov_b32_e32 v27, v2
	v_mov_b32_e32 v28, v2
	v_mov_b32_e32 v29, v2
	v_mov_b32_e32 v30, v2
	v_mov_b32_e32 v31, v2
	v_mov_b32_e32 v32, v2
	v_mov_b32_e32 v33, v2
	v_mov_b32_e32 v42, v2
	v_mov_b32_e32 v43, v2
	v_mov_b32_e32 v44, v2
	v_mov_b32_e32 v45, v2
	v_mov_b32_e32 v46, v2
	v_mov_b32_e32 v47, v2
	v_mov_b32_e32 v48, v2
	v_mov_b32_e32 v49, v2
	v_mov_b32_e32 v58, v2
	v_mov_b32_e32 v59, v2
	v_mov_b32_e32 v60, v2
	v_mov_b32_e32 v61, v2
	v_mov_b32_e32 v62, v2
	v_mov_b32_e32 v63, v2
	v_mov_b32_e32 v64, v2
	v_mov_b32_e32 v65, v2
	v_mov_b32_e32 v66, v2
	v_mov_b32_e32 v67, v2
	v_mov_b32_e32 v68, v2
	v_mov_b32_e32 v69, v2
	v_mov_b32_e32 v70, v2
	v_mov_b32_e32 v71, v2
	v_mov_b32_e32 v72, v2
	v_mov_b32_e32 v73, v2
	v_mov_b32_e32 v82, v2
	v_mov_b32_e32 v83, v2
	v_mov_b32_e32 v84, v2
	v_mov_b32_e32 v85, v2
	v_mov_b32_e32 v86, v2
	v_mov_b32_e32 v87, v2
	v_mov_b32_e32 v88, v2
	v_mov_b32_e32 v89, v2
	v_mov_b32_e32 v98, v2
	v_mov_b32_e32 v99, v2
	v_mov_b32_e32 v100, v2
	v_mov_b32_e32 v101, v2
	v_mov_b32_e32 v102, v2
	v_mov_b32_e32 v103, v2
	v_mov_b32_e32 v104, v2
	v_mov_b32_e32 v105, v2
	v_mov_b32_e32 v114, v2
	v_mov_b32_e32 v115, v2
	v_mov_b32_e32 v116, v2
	v_mov_b32_e32 v117, v2
	v_mov_b32_e32 v118, v2
	v_mov_b32_e32 v119, v2
	v_mov_b32_e32 v120, v2
	v_mov_b32_e32 v121, v2
	v_mov_b32_e32 v74, v2
	v_mov_b32_e32 v75, v2
	v_mov_b32_e32 v76, v2
	v_mov_b32_e32 v77, v2
	v_mov_b32_e32 v78, v2
	v_mov_b32_e32 v79, v2
	v_mov_b32_e32 v80, v2
	v_mov_b32_e32 v81, v2
	v_mov_b32_e32 v90, v2
	v_mov_b32_e32 v91, v2
	v_mov_b32_e32 v92, v2
	v_mov_b32_e32 v93, v2
	v_mov_b32_e32 v94, v2
	v_mov_b32_e32 v95, v2
	v_mov_b32_e32 v96, v2
	v_mov_b32_e32 v97, v2
	v_mov_b32_e32 v106, v2
	v_mov_b32_e32 v107, v2
	v_mov_b32_e32 v108, v2
	v_mov_b32_e32 v109, v2
	v_mov_b32_e32 v110, v2
	v_mov_b32_e32 v111, v2
	v_mov_b32_e32 v112, v2
	v_mov_b32_e32 v113, v2
	v_mov_b32_e32 v122, v2
	v_mov_b32_e32 v123, v2
	v_mov_b32_e32 v124, v2
	v_mov_b32_e32 v125, v2
	v_mov_b32_e32 v126, v2
	v_mov_b32_e32 v127, v2
	v_mov_b32_e32 v128, v2
	v_mov_b32_e32 v129, v2
	s_cmp_eq_u32 s26, 1
	s_cbranch_scc1 .LBB0_1474
.Lp9_peel:
	ds_read_b128 v[152:155], v149
	ds_read_b128 v[156:159], v149 offset:1024
	ds_read_b128 v[160:163], v149 offset:2048
	ds_read_b128 v[164:167], v149 offset:3072
	ds_read_b128 v[168:171], v150
	ds_read_b128 v[172:175], v150 offset:1024
	ds_read_b128 v[176:179], v150 offset:2048
	ds_read_b128 v[180:183], v150 offset:3072
	s_add_u32 s8, s56, 0xfffc0080
	s_addc_u32 s9, s57, -1
	s_cmp_eq_u32 s69, 12
	s_cselect_b32 s61, s49, s9
	s_cselect_b32 s60, s65, s8
	s_cselect_b32 s59, s47, s68
	s_cselect_b32 s58, s66, s67
	v_lshl_add_u64 v[146:147], s[56:57], 0, v[138:139]
	s_add_i32 m0, s85, 0xc000
	ds_read_b128 v[184:187], v151
	ds_read_b128 v[188:191], v151 offset:1024
	ds_read_b128 v[192:195], v151 offset:2048
	ds_read_b128 v[196:199], v151 offset:3072
	ds_read_b128 v[200:203], v151 offset:4096
	ds_read_b128 v[204:207], v151 offset:5120
	ds_read_b128 v[208:211], v151 offset:6144
	ds_read_b128 v[212:215], v151 offset:7168
	global_load_lds_dwordx4 v[146:147], off
	v_lshl_add_u64 v[146:147], s[56:57], 0, v[140:141]
	s_add_i32 m0, s85, 0xe000
	s_nop 0
	global_load_lds_dwordx4 v[146:147], off
	s_waitcnt vmcnt(24)
	s_waitcnt lgkmcnt(0)
	s_barrier
; #define PG8_STAGE(bufoff, gbase, voff) do { _Pragma("unroll") for (int _i = 0; _i < 2; ++_i) \
;         __builtin_amdgcn_global_load_lds((const unsigned*)((const char*)(gbase) + (voff)[_i]), (PG8_LAS unsigned*)(lds + (bufoff) + ldsw + _i * 8192), 16, 0, 0); } while (0)
; #define PG8_LDA(dst, b, h) do { _Pragma("unroll") for (int m = 0; m < 4; ++m) _Pragma("unroll") for (int k = 0; k < 2; ++k) dst[m][k] = *(const PG8_LAS bf16x8*)(lds + PG8_SA(b, h) + aoff + m * 2048 + k * 1024); } while (0)
; #define PG8_MMA(ai, bj, At, Bt) do { __builtin_amdgcn_s_setprio(1); _Pragma("unroll") for (int m = 0; m < 4; ++m) _Pragma("unroll") for (int n = 0; n < 2; ++n) _Pragma("unroll") for (int k = 0; k < 2; ++k) \
;         acc[ai][bj][m][n] = __builtin_amdgcn_mfma_f32_16x16x32_bf16(Bt[n][k], At[m][k], acc[ai][bj][m][n], 0, 0, 0); __builtin_amdgcn_s_setprio(0); } while (0)
; #define PG8_WAIT_V(n) asm volatile("s_waitcnt vmcnt(" #n ")" ::: "memory")
; #define PG8_WAIT_L(n) asm volatile("s_waitcnt lgkmcnt(" #n ")" ::: "memory")
; #define PG8_BAR __builtin_amdgcn_s_barrier()
; #define PG8_SCHED __builtin_amdgcn_sched_barrier(0)
; template <class Epi, class Sched, bool ALIGN_EPI = false, bool SP2 = false>
; __device__ __forceinline__ void gemm_phase(PG8_LAS unsigned char* lds, const Gemm g, const Sched& S, const Epi& E, const int wid) {
;     ...
;             PG8_WAIT_V(8); PG8_WAIT_L(0); PG8_BAR; PG8_MMA(0, 0, At, B0); PG8_MMA(0, 1, At, B1); PG8_BAR; PG8_SCHED;
;             PG8_LDA(At, 0, 1); PG8_STAGE(PG8_SB(0, 0), b2, voffB); PG8_STAGE(PG8_SB(0, 1), b2 + hsB, voffB); PG8_STAGE(PG8_SA(0, 0), a2, voffA);
;             PG8_WAIT_V(8); PG8_WAIT_L(0); PG8_BAR; PG8_MMA(1, 0, At, B0); PG8_MMA(1, 1, At, B1); PG8_BAR; PG8_SCHED;
	s_setprio 1
	s_waitcnt lgkmcnt(0)
	v_mfma_f32_16x16x32_bf16 v[126:129], v[152:155], v[184:187], v[126:129]
	v_mfma_f32_16x16x32_bf16 v[122:125], v[160:163], v[184:187], v[122:125]
	v_mfma_f32_16x16x32_bf16 v[110:113], v[152:155], v[192:195], v[110:113]
	v_mfma_f32_16x16x32_bf16 v[106:109], v[160:163], v[192:195], v[106:109]
	v_mfma_f32_16x16x32_bf16 v[94:97], v[152:155], v[200:203], v[94:97]
	v_mfma_f32_16x16x32_bf16 v[90:93], v[160:163], v[200:203], v[90:93]
	v_mfma_f32_16x16x32_bf16 v[78:81], v[152:155], v[208:211], v[78:81]
	v_mfma_f32_16x16x32_bf16 v[74:77], v[160:163], v[208:211], v[74:77]
	v_mfma_f32_16x16x32_bf16 v[126:129], v[156:159], v[188:191], v[126:129]
	v_mfma_f32_16x16x32_bf16 v[122:125], v[164:167], v[188:191], v[122:125]
	v_mfma_f32_16x16x32_bf16 v[110:113], v[156:159], v[196:199], v[110:113]
	v_mfma_f32_16x16x32_bf16 v[106:109], v[164:167], v[196:199], v[106:109]
	v_mfma_f32_16x16x32_bf16 v[94:97], v[156:159], v[204:207], v[94:97]
	v_mfma_f32_16x16x32_bf16 v[90:93], v[164:167], v[204:207], v[90:93]
	v_mfma_f32_16x16x32_bf16 v[78:81], v[156:159], v[212:215], v[78:81]
	v_mfma_f32_16x16x32_bf16 v[74:77], v[164:167], v[212:215], v[74:77]
	s_setprio 0
	s_setprio 1
	v_mfma_f32_16x16x32_bf16 v[118:121], v[168:171], v[184:187], v[118:121]
	v_mfma_f32_16x16x32_bf16 v[114:117], v[176:179], v[184:187], v[114:117]
	v_mfma_f32_16x16x32_bf16 v[102:105], v[168:171], v[192:195], v[102:105]
	v_mfma_f32_16x16x32_bf16 v[98:101], v[176:179], v[192:195], v[98:101]
	v_mfma_f32_16x16x32_bf16 v[86:89], v[168:171], v[200:203], v[86:89]
	v_mfma_f32_16x16x32_bf16 v[82:85], v[176:179], v[200:203], v[82:85]
	v_mfma_f32_16x16x32_bf16 v[70:73], v[168:171], v[208:211], v[70:73]
	v_mfma_f32_16x16x32_bf16 v[66:69], v[176:179], v[208:211], v[66:69]
	v_mfma_f32_16x16x32_bf16 v[118:121], v[172:175], v[188:191], v[118:121]
	v_mfma_f32_16x16x32_bf16 v[114:117], v[180:183], v[188:191], v[114:117]
	v_mfma_f32_16x16x32_bf16 v[102:105], v[172:175], v[196:199], v[102:105]
	v_mfma_f32_16x16x32_bf16 v[98:101], v[180:183], v[196:199], v[98:101]
	v_mfma_f32_16x16x32_bf16 v[86:89], v[172:175], v[204:207], v[86:89]
	v_mfma_f32_16x16x32_bf16 v[82:85], v[180:183], v[204:207], v[82:85]
	v_mfma_f32_16x16x32_bf16 v[70:73], v[172:175], v[212:215], v[70:73]
	v_mfma_f32_16x16x32_bf16 v[66:69], v[180:183], v[212:215], v[66:69]
	s_setprio 0
	s_barrier
	s_add_i32 s8, s35, s28
	v_lshl_add_u64 v[146:147], s[58:59], 0, v[134:135]
	s_mov_b32 m0, s8
	ds_read_b128 v[184:187], v151 offset:16384
	ds_read_b128 v[188:191], v151 offset:17408
	ds_read_b128 v[192:195], v151 offset:18432
	ds_read_b128 v[196:199], v151 offset:19456
	ds_read_b128 v[200:203], v151 offset:20480
	ds_read_b128 v[204:207], v151 offset:21504
	ds_read_b128 v[208:211], v151 offset:22528
	ds_read_b128 v[212:215], v151 offset:23552
	global_load_lds_dwordx4 v[146:147], off
	s_add_i32 m0, s8, 0x2000
	s_add_u32 s24, s58, 0x40000
	v_lshl_add_u64 v[216:217], s[58:59], 0, v[130:131]
	s_addc_u32 s25, s59, 0
	s_add_i32 s8, s36, s28
	global_load_lds_dwordx4 v[216:217], off
	v_lshl_add_u64 v[218:219], s[24:25], 0, v[134:135]
	s_mov_b32 m0, s8
	v_lshl_add_u64 v[220:221], s[60:61], 0, v[132:133]
	global_load_lds_dwordx4 v[218:219], off
	v_lshl_add_u64 v[218:219], s[24:25], 0, v[130:131]
	s_add_i32 m0, s8, 0x2000
	s_nop 0
	global_load_lds_dwordx4 v[218:219], off
	v_lshl_add_u64 v[218:219], s[60:61], 0, v[136:137]
	s_mov_b32 m0, s85
	s_nop 0
	global_load_lds_dwordx4 v[218:219], off
	s_mov_b32 m0, s17
	s_nop 0
	global_load_lds_dwordx4 v[220:221], off
	s_waitcnt vmcnt(24)
	s_waitcnt lgkmcnt(0)
	s_barrier
	s_setprio 1
	s_waitcnt lgkmcnt(0)
	v_mfma_f32_16x16x32_bf16 v[62:65], v[152:155], v[184:187], v[62:65]
	v_mfma_f32_16x16x32_bf16 v[58:61], v[160:163], v[184:187], v[58:61]
	v_mfma_f32_16x16x32_bf16 v[46:49], v[152:155], v[192:195], v[46:49]
	v_mfma_f32_16x16x32_bf16 v[42:45], v[160:163], v[192:195], v[42:45]
	v_mfma_f32_16x16x32_bf16 v[30:33], v[152:155], v[200:203], v[30:33]
	v_mfma_f32_16x16x32_bf16 v[26:29], v[160:163], v[200:203], v[26:29]
	v_mfma_f32_16x16x32_bf16 v[14:17], v[152:155], v[208:211], v[14:17]
	v_mfma_f32_16x16x32_bf16 v[10:13], v[160:163], v[208:211], v[10:13]
	v_mfma_f32_16x16x32_bf16 v[62:65], v[156:159], v[188:191], v[62:65]
	v_mfma_f32_16x16x32_bf16 v[58:61], v[164:167], v[188:191], v[58:61]
	v_mfma_f32_16x16x32_bf16 v[46:49], v[156:159], v[196:199], v[46:49]
	v_mfma_f32_16x16x32_bf16 v[42:45], v[164:167], v[196:199], v[42:45]
	v_mfma_f32_16x16x32_bf16 v[30:33], v[156:159], v[204:207], v[30:33]
	v_mfma_f32_16x16x32_bf16 v[26:29], v[164:167], v[204:207], v[26:29]
	v_mfma_f32_16x16x32_bf16 v[14:17], v[156:159], v[212:215], v[14:17]
	v_mfma_f32_16x16x32_bf16 v[10:13], v[164:167], v[212:215], v[10:13]
	s_setprio 0
	s_setprio 1
	v_mfma_f32_16x16x32_bf16 v[54:57], v[168:171], v[184:187], v[54:57]
	v_mfma_f32_16x16x32_bf16 v[50:53], v[176:179], v[184:187], v[50:53]
	v_mfma_f32_16x16x32_bf16 v[38:41], v[168:171], v[192:195], v[38:41]
	v_mfma_f32_16x16x32_bf16 v[34:37], v[176:179], v[192:195], v[34:37]
	v_mfma_f32_16x16x32_bf16 v[22:25], v[168:171], v[200:203], v[22:25]
	v_mfma_f32_16x16x32_bf16 v[18:21], v[176:179], v[200:203], v[18:21]
	v_mfma_f32_16x16x32_bf16 v[6:9], v[168:171], v[208:211], v[6:9]
	v_mfma_f32_16x16x32_bf16 v[2:5], v[176:179], v[208:211], v[2:5]
	v_mfma_f32_16x16x32_bf16 v[54:57], v[172:175], v[188:191], v[54:57]
	v_mfma_f32_16x16x32_bf16 v[50:53], v[180:183], v[188:191], v[50:53]
	v_mfma_f32_16x16x32_bf16 v[38:41], v[172:175], v[196:199], v[38:41]
	v_mfma_f32_16x16x32_bf16 v[34:37], v[180:183], v[196:199], v[34:37]
	v_mfma_f32_16x16x32_bf16 v[22:25], v[172:175], v[204:207], v[22:25]
	v_mfma_f32_16x16x32_bf16 v[18:21], v[180:183], v[204:207], v[18:21]
	v_mfma_f32_16x16x32_bf16 v[6:9], v[172:175], v[212:215], v[6:9]
	v_mfma_f32_16x16x32_bf16 v[2:5], v[180:183], v[212:215], v[2:5]
	s_setprio 0
	s_barrier
; #define PG8_STAGE(bufoff, gbase, voff) do { _Pragma("unroll") for (int _i = 0; _i < 2; ++_i) \
;         __builtin_amdgcn_global_load_lds((const unsigned*)((const char*)(gbase) + (voff)[_i]), (PG8_LAS unsigned*)(lds + (bufoff) + ldsw + _i * 8192), 16, 0, 0); } while (0)
; #define PG8_LDA(dst, b, h) do { _Pragma("unroll") for (int m = 0; m < 4; ++m) _Pragma("unroll") for (int k = 0; k < 2; ++k) dst[m][k] = *(const PG8_LAS bf16x8*)(lds + PG8_SA(b, h) + aoff + m * 2048 + k * 1024); } while (0)
; #define PG8_LDB(dst, b, h) do { _Pragma("unroll") for (int n = 0; n < 2; ++n) _Pragma("unroll") for (int k = 0; k < 2; ++k) dst[n][k] = *(const PG8_LAS bf16x8*)(lds + PG8_SB(b, h) + boff + n * 2048 + k * 1024); } while (0)
; #define PG8_MMA(ai, bj, At, Bt) do { __builtin_amdgcn_s_setprio(1); _Pragma("unroll") for (int m = 0; m < 4; ++m) _Pragma("unroll") for (int n = 0; n < 2; ++n) _Pragma("unroll") for (int k = 0; k < 2; ++k) \
;         acc[ai][bj][m][n] = __builtin_amdgcn_mfma_f32_16x16x32_bf16(Bt[n][k], At[m][k], acc[ai][bj][m][n], 0, 0, 0); __builtin_amdgcn_s_setprio(0); } while (0)
; #define PG8_WAIT_V(n) asm volatile("s_waitcnt vmcnt(" #n ")" ::: "memory")
; #define PG8_WAIT_L(n) asm volatile("s_waitcnt lgkmcnt(" #n ")" ::: "memory")
; #define PG8_BAR __builtin_amdgcn_s_barrier()
; #define PG8_SCHED __builtin_amdgcn_sched_barrier(0)
; template <class Epi, class Sched, bool ALIGN_EPI = false, bool SP2 = false>
; __device__ __forceinline__ void gemm_phase(PG8_LAS unsigned char* lds, const Gemm g, const Sched& S, const Epi& E, const int wid) {
;     ...
;             PG8_LDB(B0, 1, 0); PG8_LDB(B1, 1, 1); PG8_SCHED; PG8_LDA(At, 1, 0); PG8_STAGE(PG8_SA(0, 1), a2 + hsA, voffA);
;             PG8_WAIT_V(8); PG8_WAIT_L(0); PG8_BAR; PG8_MMA(0, 0, At, B0); PG8_MMA(0, 1, At, B1); PG8_BAR; PG8_SCHED;
	s_add_i32 s8, 0, 0x18000
	s_add_i32 s9, 0, 0x1c000
	v_add_u32_e32 v164, s8, v148
	v_add_u32_e32 v180, s9, v148
	ds_read_b128 v[152:155], v164
	ds_read_b128 v[156:159], v164 offset:1024
	ds_read_b128 v[160:163], v164 offset:2048
	ds_read_b128 v[164:167], v164 offset:3072
	ds_read_b128 v[168:171], v180
	ds_read_b128 v[172:175], v180 offset:1024
	ds_read_b128 v[176:179], v180 offset:2048
	ds_read_b128 v[180:183], v180 offset:3072
	s_add_u32 s24, s60, 0x40000
	s_addc_u32 s25, s61, 0
	s_mov_b32 m0, s18
	v_lshl_add_u64 v[222:223], s[24:25], 0, v[136:137]
	ds_read_b128 v[184:187], v151 offset:32768
	ds_read_b128 v[188:191], v151 offset:33792
	ds_read_b128 v[192:195], v151 offset:34816
	ds_read_b128 v[196:199], v151 offset:35840
	ds_read_b128 v[200:203], v151 offset:36864
	ds_read_b128 v[204:207], v151 offset:37888
	ds_read_b128 v[208:211], v151 offset:38912
	ds_read_b128 v[212:215], v151 offset:39936
	global_load_lds_dwordx4 v[222:223], off
	v_lshl_add_u64 v[222:223], s[24:25], 0, v[132:133]
	s_mov_b32 m0, s19
	s_nop 0
	global_load_lds_dwordx4 v[222:223], off
	s_waitcnt vmcnt(8)
	s_waitcnt lgkmcnt(0)
	s_barrier
	s_setprio 1
	s_waitcnt lgkmcnt(0)
	v_mfma_f32_16x16x32_bf16 v[126:129], v[152:155], v[184:187], v[126:129]
	v_mfma_f32_16x16x32_bf16 v[122:125], v[160:163], v[184:187], v[122:125]
	v_mfma_f32_16x16x32_bf16 v[110:113], v[152:155], v[192:195], v[110:113]
	v_mfma_f32_16x16x32_bf16 v[106:109], v[160:163], v[192:195], v[106:109]
	v_mfma_f32_16x16x32_bf16 v[94:97], v[152:155], v[200:203], v[94:97]
	v_mfma_f32_16x16x32_bf16 v[90:93], v[160:163], v[200:203], v[90:93]
	v_mfma_f32_16x16x32_bf16 v[78:81], v[152:155], v[208:211], v[78:81]
	v_mfma_f32_16x16x32_bf16 v[74:77], v[160:163], v[208:211], v[74:77]
	v_mfma_f32_16x16x32_bf16 v[126:129], v[156:159], v[188:191], v[126:129]
	v_mfma_f32_16x16x32_bf16 v[122:125], v[164:167], v[188:191], v[122:125]
	v_mfma_f32_16x16x32_bf16 v[110:113], v[156:159], v[196:199], v[110:113]
	v_mfma_f32_16x16x32_bf16 v[106:109], v[164:167], v[196:199], v[106:109]
	v_mfma_f32_16x16x32_bf16 v[94:97], v[156:159], v[204:207], v[94:97]
	v_mfma_f32_16x16x32_bf16 v[90:93], v[164:167], v[204:207], v[90:93]
	v_mfma_f32_16x16x32_bf16 v[78:81], v[156:159], v[212:215], v[78:81]
	v_mfma_f32_16x16x32_bf16 v[74:77], v[164:167], v[212:215], v[74:77]
	s_setprio 0
	s_setprio 1
	v_mfma_f32_16x16x32_bf16 v[118:121], v[168:171], v[184:187], v[118:121]
	v_mfma_f32_16x16x32_bf16 v[114:117], v[176:179], v[184:187], v[114:117]
	v_mfma_f32_16x16x32_bf16 v[102:105], v[168:171], v[192:195], v[102:105]
	v_mfma_f32_16x16x32_bf16 v[98:101], v[176:179], v[192:195], v[98:101]
	v_mfma_f32_16x16x32_bf16 v[86:89], v[168:171], v[200:203], v[86:89]
	v_mfma_f32_16x16x32_bf16 v[82:85], v[176:179], v[200:203], v[82:85]
	v_mfma_f32_16x16x32_bf16 v[70:73], v[168:171], v[208:211], v[70:73]
	v_mfma_f32_16x16x32_bf16 v[66:69], v[176:179], v[208:211], v[66:69]
	v_mfma_f32_16x16x32_bf16 v[118:121], v[172:175], v[188:191], v[118:121]
	v_mfma_f32_16x16x32_bf16 v[114:117], v[180:183], v[188:191], v[114:117]
	v_mfma_f32_16x16x32_bf16 v[102:105], v[172:175], v[196:199], v[102:105]
	v_mfma_f32_16x16x32_bf16 v[98:101], v[180:183], v[196:199], v[98:101]
	v_mfma_f32_16x16x32_bf16 v[86:89], v[172:175], v[204:207], v[86:89]
	v_mfma_f32_16x16x32_bf16 v[82:85], v[180:183], v[204:207], v[82:85]
	v_mfma_f32_16x16x32_bf16 v[70:73], v[172:175], v[212:215], v[70:73]
	v_mfma_f32_16x16x32_bf16 v[66:69], v[180:183], v[212:215], v[66:69]
	s_setprio 0
	s_barrier
; #define PG8_STAGE(bufoff, gbase, voff) do { _Pragma("unroll") for (int _i = 0; _i < 2; ++_i) \
;         __builtin_amdgcn_global_load_lds((const unsigned*)((const char*)(gbase) + (voff)[_i]), (PG8_LAS unsigned*)(lds + (bufoff) + ldsw + _i * 8192), 16, 0, 0); } while (0)
; #define PG8_LDA(dst, b, h) do { _Pragma("unroll") for (int m = 0; m < 4; ++m) _Pragma("unroll") for (int k = 0; k < 2; ++k) dst[m][k] = *(const PG8_LAS bf16x8*)(lds + PG8_SA(b, h) + aoff + m * 2048 + k * 1024); } while (0)
; #define PG8_LDB(dst, b, h) do { _Pragma("unroll") for (int n = 0; n < 2; ++n) _Pragma("unroll") for (int k = 0; k < 2; ++k) dst[n][k] = *(const PG8_LAS bf16x8*)(lds + PG8_SB(b, h) + boff + n * 2048 + k * 1024); } while (0)
; template <class Epi, class Sched, bool ALIGN_EPI = false, bool SP2 = false>
; __device__ __forceinline__ void gemm_phase(PG8_LAS unsigned char* lds, const Gemm g, const Sched& S, const Epi& E, const int wid) {
;     ...
;         for (int t = 0; t < nt; t += 2) {
;             const bool last = (t == nt - 2);
;             const char* a1 = cA + (size_t)(t + 1) * kstep;
;             const char* a2 = last ? nA : cA + (size_t)(t + 2) * kstep; const char* b2 = last ? nB : cB + (size_t)(t + 2) * kstep;
;             const char* a3 = a2 + kstep; const char* b3 = b2 + kstep;
;             if (last && has_next) S.a_ready(nxt);
;             if constexpr (SP2) {
;             PG8_LDB(B0, 0, 0); PG8_LDB(B1, 0, 1); PG8_SCHED; PG8_LDA(At, 0, 0); PG8_STAGE(PG8_SA(1, 1), a1 + hsA, voffA);
;             PG8_WAIT_V(8); PG8_WAIT_L(0); PG8_BAR; PG8_MMA(0, 0, At, B0); PG8_MMA(0, 1, At, B1); PG8_BAR; PG8_SCHED;
;             PG8_LDA(At, 0, 1); PG8_STAGE(PG8_SB(0, 0), b2, voffB); PG8_STAGE(PG8_SB(0, 1), b2 + hsB, voffB); PG8_STAGE(PG8_SA(0, 0), a2, voffA);
;             PG8_WAIT_V(8); PG8_WAIT_L(0); PG8_BAR; PG8_MMA(1, 0, At, B0); PG8_MMA(1, 1, At, B1); PG8_BAR; PG8_SCHED;
;             PG8_LDB(B0, 1, 0); PG8_LDB(B1, 1, 1); PG8_SCHED; PG8_LDA(At, 1, 0); PG8_STAGE(PG8_SA(0, 1), a2 + hsA, voffA);
;             PG8_WAIT_V(8); PG8_WAIT_L(0); PG8_BAR; PG8_MMA(0, 0, At, B0); PG8_MMA(0, 1, At, B1); PG8_BAR; PG8_SCHED;
;             PG8_LDA(At, 1, 1); PG8_STAGE(PG8_SB(1, 0), b3, voffB); PG8_STAGE(PG8_SB(1, 1), b3 + hsB, voffB); PG8_STAGE(PG8_SA(1, 0), a3, voffA);
;             PG8_WAIT_V(8); PG8_WAIT_L(0); PG8_BAR; PG8_MMA(1, 0, At, B0); PG8_MMA(1, 1, At, B1); PG8_BAR; PG8_SCHED;
	s_add_i32 s8, s8, s28
	v_lshl_add_u64 v[146:147], v[146:147], 0, s[20:21]
	s_mov_b32 m0, s8
	ds_read_b128 v[184:187], v151 offset:49152
	ds_read_b128 v[188:191], v151 offset:50176
	ds_read_b128 v[192:195], v151 offset:51200
	ds_read_b128 v[196:199], v151 offset:52224
	ds_read_b128 v[200:203], v151 offset:53248
	ds_read_b128 v[204:207], v151 offset:54272
	ds_read_b128 v[208:211], v151 offset:55296
	ds_read_b128 v[212:215], v151 offset:56320
	global_load_lds_dwordx4 v[146:147], off
	s_add_i32 m0, s8, 0x2000
	s_add_u32 s24, s58, 0x40080
	v_lshl_add_u64 v[146:147], v[216:217], 0, s[20:21]
	s_addc_u32 s25, s59, 0
	s_add_i32 s8, s9, s28
	global_load_lds_dwordx4 v[146:147], off
	v_lshl_add_u64 v[146:147], s[24:25], 0, v[134:135]
	s_mov_b32 m0, s8
	s_nop 0
	global_load_lds_dwordx4 v[146:147], off
	v_lshl_add_u64 v[146:147], s[24:25], 0, v[130:131]
	s_add_i32 m0, s8, 0x2000
	s_nop 0
	global_load_lds_dwordx4 v[146:147], off
	v_lshl_add_u64 v[146:147], v[218:219], 0, s[20:21]
	s_mov_b32 m0, s27
	s_nop 0
	global_load_lds_dwordx4 v[146:147], off
	v_lshl_add_u64 v[146:147], v[220:221], 0, s[20:21]
	s_mov_b32 m0, s31
	s_nop 0
	global_load_lds_dwordx4 v[146:147], off
	s_waitcnt vmcnt(8)
	s_waitcnt lgkmcnt(0)
	s_barrier
	s_setprio 1
	s_waitcnt lgkmcnt(0)
	v_mfma_f32_16x16x32_bf16 v[62:65], v[152:155], v[184:187], v[62:65]
	v_mfma_f32_16x16x32_bf16 v[58:61], v[160:163], v[184:187], v[58:61]
	v_mfma_f32_16x16x32_bf16 v[46:49], v[152:155], v[192:195], v[46:49]
	v_mfma_f32_16x16x32_bf16 v[42:45], v[160:163], v[192:195], v[42:45]
	v_mfma_f32_16x16x32_bf16 v[30:33], v[152:155], v[200:203], v[30:33]
	v_mfma_f32_16x16x32_bf16 v[26:29], v[160:163], v[200:203], v[26:29]
	v_mfma_f32_16x16x32_bf16 v[14:17], v[152:155], v[208:211], v[14:17]
	v_mfma_f32_16x16x32_bf16 v[10:13], v[160:163], v[208:211], v[10:13]
	v_mfma_f32_16x16x32_bf16 v[62:65], v[156:159], v[188:191], v[62:65]
	v_mfma_f32_16x16x32_bf16 v[58:61], v[164:167], v[188:191], v[58:61]
	v_mfma_f32_16x16x32_bf16 v[46:49], v[156:159], v[196:199], v[46:49]
	v_mfma_f32_16x16x32_bf16 v[42:45], v[164:167], v[196:199], v[42:45]
	v_mfma_f32_16x16x32_bf16 v[30:33], v[156:159], v[204:207], v[30:33]
	v_mfma_f32_16x16x32_bf16 v[26:29], v[164:167], v[204:207], v[26:29]
	v_mfma_f32_16x16x32_bf16 v[14:17], v[156:159], v[212:215], v[14:17]
	v_mfma_f32_16x16x32_bf16 v[10:13], v[164:167], v[212:215], v[10:13]
	s_setprio 0
	s_setprio 1
	v_mfma_f32_16x16x32_bf16 v[54:57], v[168:171], v[184:187], v[54:57]
	v_mfma_f32_16x16x32_bf16 v[50:53], v[176:179], v[184:187], v[50:53]
	v_mfma_f32_16x16x32_bf16 v[38:41], v[168:171], v[192:195], v[38:41]
	v_mfma_f32_16x16x32_bf16 v[34:37], v[176:179], v[192:195], v[34:37]
	v_mfma_f32_16x16x32_bf16 v[22:25], v[168:171], v[200:203], v[22:25]
	v_mfma_f32_16x16x32_bf16 v[18:21], v[176:179], v[200:203], v[18:21]
	v_mfma_f32_16x16x32_bf16 v[6:9], v[168:171], v[208:211], v[6:9]
	v_mfma_f32_16x16x32_bf16 v[2:5], v[176:179], v[208:211], v[2:5]
	v_mfma_f32_16x16x32_bf16 v[54:57], v[172:175], v[188:191], v[54:57]
	v_mfma_f32_16x16x32_bf16 v[50:53], v[180:183], v[188:191], v[50:53]
	v_mfma_f32_16x16x32_bf16 v[38:41], v[172:175], v[196:199], v[38:41]
	v_mfma_f32_16x16x32_bf16 v[34:37], v[180:183], v[196:199], v[34:37]
	v_mfma_f32_16x16x32_bf16 v[22:25], v[172:175], v[204:207], v[22:25]
	v_mfma_f32_16x16x32_bf16 v[18:21], v[180:183], v[204:207], v[18:21]
	v_mfma_f32_16x16x32_bf16 v[6:9], v[172:175], v[212:215], v[6:9]
	v_mfma_f32_16x16x32_bf16 v[2:5], v[180:183], v[212:215], v[2:5]
	s_setprio 0
	s_barrier
	s_add_i32 s69, s69, 2
	s_add_u32 s56, s56, 0x100
	s_addc_u32 s57, s57, 0
	s_add_u32 s67, s67, 0x100
	s_addc_u32 s68, s68, 0
	s_cmp_gt_u32 s69, 13
	s_cbranch_scc0 .LBB0_1474
	s_branch .Lp9_exit

; #define PG8_BAR __builtin_amdgcn_s_barrier()
; template <class Epi, class Sched, bool ALIGN_EPI = false, bool SP2 = false>
; __device__ __forceinline__ void gemm_phase(PG8_LAS unsigned char* lds, const Gemm g, const Sched& S, const Epi& E, const int wid) {
;     ...
;         if constexpr (ALIGN_EPI) { if (wr == 0) PG8_BAR; }
;         { int lane_; asm volatile("v_mbcnt_lo_u32_b32 %0, -1, 0\n\tv_mbcnt_hi_u32_b32 %0, -1, %0" : "=v"(lane_)); E(acc, cur, wr, wc, lane_ & 15, lane_ >> 4); } S.done(cur);
.Lp9_exit:
	s_and_b64 vcc, exec, s[6:7]
	s_cbranch_vccz .LBB0_1477
	s_barrier
